# v31 with the GEMM K-loop heads and the attention tile loop head aligned to 256 bytes
# speedup vs baseline: 1.0151x; 1.0003x over previous
;     DI bool next(int i, pg8::Unit& o) const { if (i == 0 && have) { o = u; return true; } return false; }
; template <class Epi, class Sched, bool ALIGN_EPI = false, bool SP2 = false>
; __device__ __forceinline__ void gemm_phase(PG8_LAS unsigned char* lds, const Gemm g, const Sched& S, const Epi& E, const int tid) {
;     ...
;         const bool has_next = S.next(ui + 1, nxt);
;         const char* nA = has_next ? (const char*)g.A + (size_t)nxt.pm * tstep : cA; const char* nB = has_next ? (const char*)g.Bt + (size_t)nxt.pn * tstep : cB;
;         for (int t = 0; t < nt; t += 2) {
;             const bool last = (t == nt - 2);
;             const char* a1 = cA + (size_t)(t + 1) * kstep;
;             const char* a2 = last ? nA : cA + (size_t)(t + 2) * kstep; const char* b2 = last ? nB : cB + (size_t)(t + 2) * kstep;
;             const char* a3 = a2 + kstep; const char* b3 = b2 + kstep;
;     ...
; #pragma unroll
;         for (int a = 0; a < 2; ++a)
; #pragma unroll
;             for (int b = 0; b < 2; ++b)
; #pragma unroll
;                 for (int m = 0; m < 4; ++m)
; #pragma unroll
;                     for (int n = 0; n < 2; ++n) acc[a][b][m][n] = (f32x4){0.f, 0.f, 0.f, 0.f};
.LBB0_125:
	s_ashr_i32 s21, s20, 31
	s_lshl_b64 s[22:23], s[20:21], 19
	s_add_u32 s22, s70, s22
	s_addc_u32 s23, s71, s23
	s_and_b64 s[24:25], s[8:9], exec
	s_cselect_b32 s1, s23, s3
	s_cselect_b32 s21, s22, s2
	s_ashr_i32 s19, s18, 31
	s_lshl_b64 s[24:25], s[18:19], 19
	s_add_u32 s24, s30, s24
	s_addc_u32 s25, s31, s25
	s_and_b64 s[28:29], s[8:9], exec
	s_cselect_b32 s19, s25, s27
	s_cselect_b32 s51, s24, s26
	s_add_u32 s2, s2, 0x40080
	s_addc_u32 s3, s3, 0
	s_add_u32 s52, s26, 0x100
	v_mov_b32_e32 v0, 0
	s_addc_u32 s53, s27, 0
	s_mov_b32 s54, -2
	v_mov_b32_e32 v1, v0
	v_mov_b32_e32 v2, v0
	v_mov_b32_e32 v3, v0
	v_mov_b32_e32 v4, v0
	v_mov_b32_e32 v5, v0
	v_mov_b32_e32 v6, v0
	v_mov_b32_e32 v7, v0
	v_mov_b32_e32 v16, v0
	v_mov_b32_e32 v17, v0
	v_mov_b32_e32 v18, v0
	v_mov_b32_e32 v19, v0
	v_mov_b32_e32 v20, v0
	v_mov_b32_e32 v21, v0
	v_mov_b32_e32 v22, v0
	v_mov_b32_e32 v23, v0
	v_mov_b32_e32 v32, v0
	v_mov_b32_e32 v33, v0
	v_mov_b32_e32 v34, v0
	v_mov_b32_e32 v35, v0
	v_mov_b32_e32 v36, v0
	v_mov_b32_e32 v37, v0
	v_mov_b32_e32 v38, v0
	v_mov_b32_e32 v39, v0
	v_mov_b32_e32 v48, v0
	v_mov_b32_e32 v49, v0
	v_mov_b32_e32 v50, v0
	v_mov_b32_e32 v51, v0
	v_mov_b32_e32 v52, v0
	v_mov_b32_e32 v53, v0
	v_mov_b32_e32 v54, v0
	v_mov_b32_e32 v55, v0
	v_mov_b32_e32 v8, v0
	v_mov_b32_e32 v9, v0
	v_mov_b32_e32 v10, v0
	v_mov_b32_e32 v11, v0
	v_mov_b32_e32 v12, v0
	v_mov_b32_e32 v13, v0
	v_mov_b32_e32 v14, v0
	v_mov_b32_e32 v15, v0
	v_mov_b32_e32 v24, v0
	v_mov_b32_e32 v25, v0
	v_mov_b32_e32 v26, v0
	v_mov_b32_e32 v27, v0
	v_mov_b32_e32 v28, v0
	v_mov_b32_e32 v29, v0
	v_mov_b32_e32 v30, v0
	v_mov_b32_e32 v31, v0
	v_mov_b32_e32 v40, v0
	v_mov_b32_e32 v41, v0
	v_mov_b32_e32 v42, v0
	v_mov_b32_e32 v43, v0
	v_mov_b32_e32 v44, v0
	v_mov_b32_e32 v45, v0
	v_mov_b32_e32 v46, v0
	v_mov_b32_e32 v47, v0
	v_mov_b32_e32 v56, v0
	v_mov_b32_e32 v57, v0
	v_mov_b32_e32 v58, v0
	v_mov_b32_e32 v59, v0
	v_mov_b32_e32 v60, v0
	v_mov_b32_e32 v61, v0
	v_mov_b32_e32 v62, v0
	v_mov_b32_e32 v63, v0
	v_mov_b32_e32 v64, v0
	v_mov_b32_e32 v65, v0
	v_mov_b32_e32 v66, v0
	v_mov_b32_e32 v67, v0
	v_mov_b32_e32 v68, v0
	v_mov_b32_e32 v69, v0
	v_mov_b32_e32 v70, v0
	v_mov_b32_e32 v71, v0
	v_mov_b32_e32 v80, v0
	v_mov_b32_e32 v81, v0
	v_mov_b32_e32 v82, v0
	v_mov_b32_e32 v83, v0
	v_mov_b32_e32 v84, v0
	v_mov_b32_e32 v85, v0
	v_mov_b32_e32 v86, v0
	v_mov_b32_e32 v87, v0
	v_mov_b32_e32 v96, v0
	v_mov_b32_e32 v97, v0
	v_mov_b32_e32 v98, v0
	v_mov_b32_e32 v99, v0
	v_mov_b32_e32 v100, v0
	v_mov_b32_e32 v101, v0
	v_mov_b32_e32 v102, v0
	v_mov_b32_e32 v103, v0
	v_mov_b32_e32 v112, v0
	v_mov_b32_e32 v113, v0
	v_mov_b32_e32 v114, v0
	v_mov_b32_e32 v115, v0
	v_mov_b32_e32 v116, v0
	v_mov_b32_e32 v117, v0
	v_mov_b32_e32 v118, v0
	v_mov_b32_e32 v119, v0
	v_mov_b32_e32 v72, v0
	v_mov_b32_e32 v73, v0
	v_mov_b32_e32 v74, v0
	v_mov_b32_e32 v75, v0
	v_mov_b32_e32 v76, v0
	v_mov_b32_e32 v77, v0
	v_mov_b32_e32 v78, v0
	v_mov_b32_e32 v79, v0
	v_mov_b32_e32 v88, v0
	v_mov_b32_e32 v89, v0
	v_mov_b32_e32 v90, v0
	v_mov_b32_e32 v91, v0
	v_mov_b32_e32 v92, v0
	v_mov_b32_e32 v93, v0
	v_mov_b32_e32 v94, v0
	v_mov_b32_e32 v95, v0
	v_mov_b32_e32 v104, v0
	v_mov_b32_e32 v105, v0
	v_mov_b32_e32 v106, v0
	v_mov_b32_e32 v107, v0
	v_mov_b32_e32 v108, v0
	v_mov_b32_e32 v109, v0
	v_mov_b32_e32 v110, v0
	v_mov_b32_e32 v111, v0
	v_mov_b32_e32 v120, v0
	v_mov_b32_e32 v121, v0
	v_mov_b32_e32 v122, v0
	v_mov_b32_e32 v123, v0
	v_mov_b32_e32 v124, v0
	v_mov_b32_e32 v125, v0
	v_mov_b32_e32 v126, v0
	v_mov_b32_e32 v127, v0
	s_mov_b64 s[60:61], 0x80
	.p2alignl 8, 3212836864

; DI void attn_unit(LAS unsigned char* lds, int tid, const bf16* __restrict__ P, const bf16* __restrict__ Vt, bf16* MG, int b, int h, int qrow0, int jt0, int jt1,
;                   float lam, float oscale, const float* subg) {
;     ...
;     const int lane = tid & 63, wave = tid >> 6, r32 = lane & 31, hi = lane >> 5;
;     const int qb = wave >> 1, m = wave & 1;
;     const int qrow = qrow0 + qb * 32 + r32;
;     bf16x8 qf[4];
; #pragma unroll
;     for (int ks = 0; ks < 4; ++ks) qf[ks] = *(const bf16x8*)(P + (size_t)qrow * NIN + h * 128 + m * 64 + ks * 16 + hi * 8);
;     f32x16 O[4];
; #pragma unroll
;     for (int es = 0; es < 4; ++es)
; #pragma unroll
;         for (int i = 0; i < 16; ++i) O[es][i] = 0.f;
;     float mrun = 0.f, lrun = 0.f;
;     u32x4 kreg[2], vreg[2];
;     const bf16* vbase = Vt + (size_t)(b * 4 + h) * 128 * NKEY;
;     ...
;     const bool halfB = wave >= 4;
;     bf16x8 pf[4];
;     f32x16 negm16;
; #pragma unroll
;     for (int i = 0; i < 16; ++i) negm16[i] = 0.f;
;     ...
;     ATT_LOADG(jt0);
;     int buf = 0, pbuf = 2;
;     for (int j = jt0; j < jt1; ++j) {
.LBB0_299:
	s_or_b64 exec, exec, s[2:3]
	s_lshl_b32 s17, s15, 7
	s_lshl_b32 s36, s17, 1
	s_mov_b64 s[40:41], s[36:37]
	v_writelane_b32 v253, s40, 6
	s_movk_i32 s15, 0x2200
	v_mad_i64_i32 v[102:103], s[2:3], v99, s15, 0
	v_writelane_b32 v253, s41, 7
	v_writelane_b32 v253, s42, 8
	v_mad_i64_i32 v[100:101], s[2:3], v100, s15, 0
	v_writelane_b32 v253, s43, 9
	s_bfe_u32 s2, s14, 0x10002
	v_writelane_b32 v253, s44, 10
	s_lshl_b32 s3, s2, 8
	v_writelane_b32 v253, s45, 11
	s_add_i32 s15, s9, s3
	s_lshl_b32 s3, s2, 12
	s_lshl_b32 s2, s2, 2
	v_writelane_b32 v253, s46, 12
	s_add_i32 s16, s12, s3
	s_add_i32 s2, s8, s2
	s_and_b32 s3, s13, 3
	v_writelane_b32 v253, s47, 13
	s_add_i32 s3, s2, s3
	v_writelane_b32 v253, s48, 14
	v_writelane_b32 v253, s49, 15
	s_add_u32 s18, s74, s36
	v_and_b32_e32 v177, 63, v98
	v_add_u32_e32 v178, v97, v176
	v_writelane_b32 v253, s50, 16
	s_addc_u32 s19, s75, 0
	v_mov_b32_e32 v97, v147
	v_and_b32_e32 v98, 7, v98
	v_writelane_b32 v253, s51, 17
	v_lshl_add_u64 v[160:161], s[18:19], 0, v[96:97]
	v_mad_i64_i32 v[96:97], s[18:19], s3, v217, v[102:103]
	v_lshlrev_b32_e32 v146, 4, v98
	v_writelane_b32 v253, s52, 18
	v_lshl_add_u64 v[96:97], v[96:97], 0, v[146:147]
	v_writelane_b32 v253, s53, 19
	v_lshl_add_u64 v[162:163], s[6:7], 0, v[96:97]
	v_mad_i64_i32 v[96:97], s[18:19], s3, v217, v[100:101]
	v_writelane_b32 v253, s54, 20
	v_lshl_add_u64 v[96:97], v[96:97], 0, v[146:147]
	v_ashrrev_i32_e32 v157, 31, v156
	v_add_f32_e32 v158, 0, v158
	s_mov_b32 s2, 1
	v_writelane_b32 v253, s55, 21
	v_lshl_add_u64 v[164:165], s[6:7], 0, v[96:97]
	s_mov_b32 s17, 0
	s_mov_b32 s21, 0
	s_mov_b32 s18, 1
	v_and_b32_e32 v209, 64, v210
	v_add_u32_e32 v209, 64, v209
	v_xor_b32_e32 v250, 32, v210
	v_cmp_lt_i32_e64 s[24:25], v250, v209
	s_nop 1
	v_cndmask_b32_e64 v209, v210, v250, s[24:25]
	v_lshlrev_b32_e32 v209, 2, v209
	.p2alignl 8, 3212836864

; template <class Epi, class Sched, bool ALIGN_EPI = false, bool SP2 = false>
; __device__ __forceinline__ void gemm_phase(PG8_LAS unsigned char* lds, const Gemm g, const Sched& S, const Epi& E, const int tid) {
;     ...
;         for (int t = 0; t < nt; t += 2) {
;             const bool last = (t == nt - 2);
;             const char* a1 = cA + (size_t)(t + 1) * kstep;
;             const char* a2 = last ? nA : cA + (size_t)(t + 2) * kstep; const char* b2 = last ? nB : cB + (size_t)(t + 2) * kstep;
;             const char* a3 = a2 + kstep; const char* b3 = b2 + kstep;
;     ...
; #pragma unroll
;         for (int a = 0; a < 2; ++a)
; #pragma unroll
;             for (int b = 0; b < 2; ++b)
; #pragma unroll
;                 for (int m = 0; m < 4; ++m)
; #pragma unroll
;                     for (int n = 0; n < 2; ++n) acc[a][b][m][n] = (f32x4){0.f, 0.f, 0.f, 0.f};
.LBB0_880:
	s_add_u32 s30, s30, 0x80
	s_addc_u32 s31, s31, 0
	s_add_u32 s57, s34, 0x100
	v_mov_b32_e32 v0, 0
	s_addc_u32 s58, s35, 0
	s_mov_b32 s34, 0
	v_mov_b32_e32 v1, v0
	v_mov_b32_e32 v2, v0
	v_mov_b32_e32 v3, v0
	v_mov_b32_e32 v4, v0
	v_mov_b32_e32 v5, v0
	v_mov_b32_e32 v6, v0
	v_mov_b32_e32 v7, v0
	v_mov_b32_e32 v8, v0
	v_mov_b32_e32 v9, v0
	v_mov_b32_e32 v10, v0
	v_mov_b32_e32 v11, v0
	v_mov_b32_e32 v12, v0
	v_mov_b32_e32 v13, v0
	v_mov_b32_e32 v14, v0
	v_mov_b32_e32 v15, v0
	v_mov_b32_e32 v16, v0
	v_mov_b32_e32 v17, v0
	v_mov_b32_e32 v18, v0
	v_mov_b32_e32 v19, v0
	v_mov_b32_e32 v20, v0
	v_mov_b32_e32 v21, v0
	v_mov_b32_e32 v22, v0
	v_mov_b32_e32 v23, v0
	v_mov_b32_e32 v24, v0
	v_mov_b32_e32 v25, v0
	v_mov_b32_e32 v26, v0
	v_mov_b32_e32 v27, v0
	v_mov_b32_e32 v28, v0
	v_mov_b32_e32 v29, v0
	v_mov_b32_e32 v30, v0
	v_mov_b32_e32 v31, v0
	v_mov_b32_e32 v64, v0
	v_mov_b32_e32 v65, v0
	v_mov_b32_e32 v66, v0
	v_mov_b32_e32 v67, v0
	v_mov_b32_e32 v68, v0
	v_mov_b32_e32 v69, v0
	v_mov_b32_e32 v70, v0
	v_mov_b32_e32 v71, v0
	v_mov_b32_e32 v72, v0
	v_mov_b32_e32 v73, v0
	v_mov_b32_e32 v74, v0
	v_mov_b32_e32 v75, v0
	v_mov_b32_e32 v76, v0
	v_mov_b32_e32 v77, v0
	v_mov_b32_e32 v78, v0
	v_mov_b32_e32 v79, v0
	v_mov_b32_e32 v80, v0
	v_mov_b32_e32 v81, v0
	v_mov_b32_e32 v82, v0
	v_mov_b32_e32 v83, v0
	v_mov_b32_e32 v84, v0
	v_mov_b32_e32 v85, v0
	v_mov_b32_e32 v86, v0
	v_mov_b32_e32 v87, v0
	v_mov_b32_e32 v88, v0
	v_mov_b32_e32 v89, v0
	v_mov_b32_e32 v90, v0
	v_mov_b32_e32 v91, v0
	v_mov_b32_e32 v92, v0
	v_mov_b32_e32 v93, v0
	v_mov_b32_e32 v94, v0
	v_mov_b32_e32 v95, v0
	v_mov_b32_e32 v32, v0
	v_mov_b32_e32 v33, v0
	v_mov_b32_e32 v34, v0
	v_mov_b32_e32 v35, v0
	v_mov_b32_e32 v36, v0
	v_mov_b32_e32 v37, v0
	v_mov_b32_e32 v38, v0
	v_mov_b32_e32 v39, v0
	v_mov_b32_e32 v40, v0
	v_mov_b32_e32 v41, v0
	v_mov_b32_e32 v42, v0
	v_mov_b32_e32 v43, v0
	v_mov_b32_e32 v44, v0
	v_mov_b32_e32 v45, v0
	v_mov_b32_e32 v46, v0
	v_mov_b32_e32 v47, v0
	v_mov_b32_e32 v48, v0
	v_mov_b32_e32 v49, v0
	v_mov_b32_e32 v50, v0
	v_mov_b32_e32 v51, v0
	v_mov_b32_e32 v52, v0
	v_mov_b32_e32 v53, v0
	v_mov_b32_e32 v54, v0
	v_mov_b32_e32 v55, v0
	v_mov_b32_e32 v56, v0
	v_mov_b32_e32 v57, v0
	v_mov_b32_e32 v58, v0
	v_mov_b32_e32 v59, v0
	v_mov_b32_e32 v60, v0
	v_mov_b32_e32 v61, v0
	v_mov_b32_e32 v62, v0
	v_mov_b32_e32 v63, v0
	v_mov_b32_e32 v96, v0
	v_mov_b32_e32 v97, v0
	v_mov_b32_e32 v98, v0
	v_mov_b32_e32 v99, v0
	v_mov_b32_e32 v100, v0
	v_mov_b32_e32 v101, v0
	v_mov_b32_e32 v102, v0
	v_mov_b32_e32 v103, v0
	v_mov_b32_e32 v104, v0
	v_mov_b32_e32 v105, v0
	v_mov_b32_e32 v106, v0
	v_mov_b32_e32 v107, v0
	v_mov_b32_e32 v108, v0
	v_mov_b32_e32 v109, v0
	v_mov_b32_e32 v110, v0
	v_mov_b32_e32 v111, v0
	v_mov_b32_e32 v112, v0
	v_mov_b32_e32 v113, v0
	v_mov_b32_e32 v114, v0
	v_mov_b32_e32 v115, v0
	v_mov_b32_e32 v116, v0
	v_mov_b32_e32 v117, v0
	v_mov_b32_e32 v118, v0
	v_mov_b32_e32 v119, v0
	v_mov_b32_e32 v120, v0
	v_mov_b32_e32 v121, v0
	v_mov_b32_e32 v122, v0
	v_mov_b32_e32 v123, v0
	v_mov_b32_e32 v124, v0
	v_mov_b32_e32 v125, v0
	v_mov_b32_e32 v126, v0
	v_mov_b32_e32 v127, v0
	s_mov_b64 s[68:69], 0x80
	.p2alignl 8, 3212836864

; #define PG8_STAGE(bufoff, gbase, voff) do { _Pragma("unroll") for (int _i = 0; _i < 2; ++_i) \
;         __builtin_amdgcn_global_load_lds((const unsigned*)((const char*)(gbase) + (voff)[_i]), (PG8_LAS unsigned*)(lds + (bufoff) + ldsw + _i * 8192), 16, 0, 0); } while (0)
; #define PG8_WAIT_V(n) asm volatile("s_waitcnt vmcnt(" #n ")" ::: "memory")
; #define PG8_BAR __builtin_amdgcn_s_barrier()
; template <class Epi, class Sched, bool ALIGN_EPI = false, bool SP2 = false>
; __device__ __forceinline__ void gemm_phase(PG8_LAS unsigned char* lds, const Gemm g, const Sched& S, const Epi& E, const int tid) {
;     ...
;         PG8_STAGE(PG8_SB(0, 0), cB, voffB); PG8_STAGE(PG8_SB(0, 1), cB + hstep, voffB); PG8_STAGE(PG8_SA(0, 0), cA, voffA); PG8_STAGE(PG8_SA(0, 1), cA + hstep, voffA);
;         if (wr == 1) PG8_BAR;
;         PG8_WAIT_V(2); PG8_BAR;
;         PG8_STAGE(PG8_SB(1, 0), cB + kstep, voffB); PG8_STAGE(PG8_SA(1, 0), cA + kstep, voffA); PG8_STAGE(PG8_SB(1, 1), cB + hstep + kstep, voffB);
;         PG8_WAIT_V(6); PG8_BAR;
; __global__ void __launch_bounds__(NTHREADS, 2) mega(Args A) {
;     ...
;                 const int kt0 = (s == 7) ? 4 * qd : (qd < 2 ? 12 * qd : 24 + 10 * (qd - 2));
;                 const int ktn = (s == 7) ? 4 : (qd < 2 ? 12 : 10);
;                 OneUnit S1u; S1u.have = sb < 128; S1u.u.pm = 128 + (sb & 7); S1u.u.pn = (sb >> 3) & 3;
;                 EpiPartial Ep{(float*)(ws + WS_T) + (size_t)qd * M_CTX * DM, modg_p, scale_v};
;                 pg8::Gemm g2{Ap + (size_t)kt0 * 64, Bp + (size_t)kt0 * 64, M_ALL, DM, ktn * 64, ldd};
.LBB0_906:
	s_lshr_b32 s20, s20, 5
	v_mov_b32_e32 v133, v147
	v_lshl_add_u64 v[4:5], s[14:15], 0, v[146:147]
	v_lshl_add_u64 v[6:7], s[14:15], 0, v[132:133]
	s_lshl_b32 s14, s20, 6
	s_and_b32 s14, s14, 0x80
	s_sub_i32 s14, 0x300, s14
	s_lshr_b32 s14, s14, 6
	v_lshl_add_u64 v[0:1], s[0:1], 0, v[146:147]
	s_and_b64 s[12:13], s[12:13], exec
	s_mov_b64 s[36:37], 0x80
	v_lshl_add_u64 v[2:3], s[0:1], 0, v[132:133]
	v_mov_b32_e32 v129, v147
	s_cselect_b32 s26, s14, 4
	s_add_i32 m0, s21, 0x18000
	v_lshl_add_u64 v[0:1], v[0:1], 0, s[36:37]
	v_lshl_add_u64 v[8:9], s[2:3], 0, v[128:129]
	v_mov_b32_e32 v131, v147
	s_lshl_b32 s20, s27, 6
	s_lshl_b32 s12, s27, 13
	s_waitcnt vmcnt(2)
	s_barrier
	global_load_lds_dwordx4 v[0:1], off
	v_lshl_add_u64 v[0:1], v[2:3], 0, s[36:37]
	s_add_i32 m0, s21, 0x1a000
	s_add_i32 s27, s21, 0x8000
	v_lshl_add_u64 v[10:11], s[2:3], 0, v[130:131]
	global_load_lds_dwordx4 v[0:1], off
	v_lshl_add_u64 v[0:1], v[8:9], 0, s[36:37]
	s_mov_b32 m0, s27
	s_add_i32 s28, s21, 0xa000
	global_load_lds_dwordx4 v[0:1], off
	v_lshl_add_u64 v[0:1], v[10:11], 0, s[36:37]
	s_mov_b32 m0, s28
	v_lshlrev_b32_e32 v13, 2, v141
	global_load_lds_dwordx4 v[0:1], off
	s_add_i32 m0, s21, 0x1c000
	v_lshl_add_u64 v[0:1], v[4:5], 0, s[36:37]
	global_load_lds_dwordx4 v[0:1], off
	v_lshl_add_u64 v[0:1], v[6:7], 0, s[36:37]
	s_add_i32 m0, s21, 0x1e000
	v_lshl_or_b32 v12, v141, 6, v221
	global_load_lds_dwordx4 v[0:1], off
	v_and_b32_e32 v13, 32, v13
	v_bitop3_b32 v12, v12, s12, v13 bitop3:0xde
	s_lshl_b32 s12, s25, 5
	s_waitcnt vmcnt(6)
	s_and_b32 s25, s12, 0x60
	v_mov_b32_e32 v0, 0
	v_readlane_b32 s40, v253, 6
	v_lshl_or_b32 v134, s25, 7, v222
	s_add_i32 s29, s26, -2
	s_mov_b32 s14, 0
	v_add_u32_e32 v135, 0, v12
	v_mov_b32_e32 v1, v0
	v_mov_b32_e32 v2, v0
	v_mov_b32_e32 v3, v0
	v_mov_b32_e32 v4, v0
	v_mov_b32_e32 v5, v0
	v_mov_b32_e32 v6, v0
	v_mov_b32_e32 v7, v0
	v_mov_b32_e32 v12, v0
	v_mov_b32_e32 v13, v0
	v_mov_b32_e32 v14, v0
	v_mov_b32_e32 v15, v0
	v_mov_b32_e32 v16, v0
	v_mov_b32_e32 v17, v0
	v_mov_b32_e32 v18, v0
	v_mov_b32_e32 v19, v0
	v_mov_b32_e32 v28, v0
	v_mov_b32_e32 v29, v0
	v_mov_b32_e32 v30, v0
	v_mov_b32_e32 v31, v0
	v_mov_b32_e32 v32, v0
	v_mov_b32_e32 v33, v0
	v_mov_b32_e32 v34, v0
	v_mov_b32_e32 v35, v0
	v_mov_b32_e32 v44, v0
	v_mov_b32_e32 v45, v0
	v_mov_b32_e32 v46, v0
	v_mov_b32_e32 v47, v0
	v_mov_b32_e32 v48, v0
	v_mov_b32_e32 v49, v0
	v_mov_b32_e32 v50, v0
	v_mov_b32_e32 v51, v0
	v_mov_b32_e32 v8, v0
	v_mov_b32_e32 v9, v0
	v_mov_b32_e32 v10, v0
	v_mov_b32_e32 v11, v0
	v_mov_b32_e32 v20, v0
	v_mov_b32_e32 v21, v0
	v_mov_b32_e32 v22, v0
	v_mov_b32_e32 v23, v0
	v_mov_b32_e32 v24, v0
	v_mov_b32_e32 v25, v0
	v_mov_b32_e32 v26, v0
	v_mov_b32_e32 v27, v0
	v_mov_b32_e32 v36, v0
	v_mov_b32_e32 v37, v0
	v_mov_b32_e32 v38, v0
	v_mov_b32_e32 v39, v0
	v_mov_b32_e32 v40, v0
	v_mov_b32_e32 v41, v0
	v_mov_b32_e32 v42, v0
	v_mov_b32_e32 v43, v0
	v_mov_b32_e32 v52, v0
	v_mov_b32_e32 v53, v0
	v_mov_b32_e32 v54, v0
	v_mov_b32_e32 v55, v0
	v_mov_b32_e32 v56, v0
	v_mov_b32_e32 v57, v0
	v_mov_b32_e32 v58, v0
	v_mov_b32_e32 v59, v0
	v_mov_b32_e32 v60, v0
	v_mov_b32_e32 v61, v0
	v_mov_b32_e32 v62, v0
	v_mov_b32_e32 v63, v0
	v_mov_b32_e32 v64, v0
	v_mov_b32_e32 v65, v0
	v_mov_b32_e32 v66, v0
	v_mov_b32_e32 v67, v0
	v_mov_b32_e32 v68, v0
	v_mov_b32_e32 v69, v0
	v_mov_b32_e32 v70, v0
	v_mov_b32_e32 v71, v0
	v_mov_b32_e32 v76, v0
	v_mov_b32_e32 v77, v0
	v_mov_b32_e32 v78, v0
	v_mov_b32_e32 v79, v0
	v_mov_b32_e32 v84, v0
	v_mov_b32_e32 v85, v0
	v_mov_b32_e32 v86, v0
	v_mov_b32_e32 v87, v0
	v_mov_b32_e32 v92, v0
	v_mov_b32_e32 v93, v0
	v_mov_b32_e32 v94, v0
	v_mov_b32_e32 v95, v0
	v_mov_b32_e32 v100, v0
	v_mov_b32_e32 v101, v0
	v_mov_b32_e32 v102, v0
	v_mov_b32_e32 v103, v0
	v_mov_b32_e32 v108, v0
	v_mov_b32_e32 v109, v0
	v_mov_b32_e32 v110, v0
	v_mov_b32_e32 v111, v0
	v_mov_b32_e32 v116, v0
	v_mov_b32_e32 v117, v0
	v_mov_b32_e32 v118, v0
	v_mov_b32_e32 v119, v0
	v_mov_b32_e32 v72, v0
	v_mov_b32_e32 v73, v0
	v_mov_b32_e32 v74, v0
	v_mov_b32_e32 v75, v0
	v_mov_b32_e32 v80, v0
	v_mov_b32_e32 v81, v0
	v_mov_b32_e32 v82, v0
	v_mov_b32_e32 v83, v0
	v_mov_b32_e32 v88, v0
	v_mov_b32_e32 v89, v0
	v_mov_b32_e32 v90, v0
	v_mov_b32_e32 v91, v0
	v_mov_b32_e32 v96, v0
	v_mov_b32_e32 v97, v0
	v_mov_b32_e32 v98, v0
	v_mov_b32_e32 v99, v0
	v_mov_b32_e32 v104, v0
	v_mov_b32_e32 v105, v0
	v_mov_b32_e32 v106, v0
	v_mov_b32_e32 v107, v0
	v_mov_b32_e32 v112, v0
	v_mov_b32_e32 v113, v0
	v_mov_b32_e32 v114, v0
	v_mov_b32_e32 v115, v0
	v_mov_b32_e32 v124, v0
	v_mov_b32_e32 v125, v0
	v_mov_b32_e32 v126, v0
	v_mov_b32_e32 v127, v0
	v_mov_b32_e32 v120, v0
	v_mov_b32_e32 v121, v0
	v_mov_b32_e32 v122, v0
	v_mov_b32_e32 v123, v0
	v_readlane_b32 s41, v253, 7
	s_barrier
	v_readlane_b32 s42, v253, 8
	v_readlane_b32 s43, v253, 9
	v_readlane_b32 s44, v253, 10
	v_readlane_b32 s45, v253, 11
	v_readlane_b32 s46, v253, 12
	v_readlane_b32 s47, v253, 13
	v_readlane_b32 s48, v253, 14
	v_readlane_b32 s49, v253, 15
	v_readlane_b32 s50, v253, 16
	v_readlane_b32 s51, v253, 17
	v_readlane_b32 s52, v253, 18
	v_readlane_b32 s53, v253, 19
	v_readlane_b32 s54, v253, 20
	v_readlane_b32 s55, v253, 21
	.p2alignl 8, 3212836864

;     DI bool next(int i, pg8::Unit& o) const { if (i == 0 && have) { o = u; return true; } return false; }
; template <class Epi, class Sched, bool ALIGN_EPI = false, bool SP2 = false>
; __device__ __forceinline__ void gemm_phase(PG8_LAS unsigned char* lds, const Gemm g, const Sched& S, const Epi& E, const int tid) {
;     ...
;         const bool has_next = S.next(ui + 1, nxt);
;         const char* nA = has_next ? (const char*)g.A + (size_t)nxt.pm * tstep : cA; const char* nB = has_next ? (const char*)g.Bt + (size_t)nxt.pn * tstep : cB;
;         for (int t = 0; t < nt; t += 2) {
;             const bool last = (t == nt - 2);
;             const char* a1 = cA + (size_t)(t + 1) * kstep;
;             const char* a2 = last ? nA : cA + (size_t)(t + 2) * kstep; const char* b2 = last ? nB : cB + (size_t)(t + 2) * kstep;
;             const char* a3 = a2 + kstep; const char* b3 = b2 + kstep;
;     ...
; #pragma unroll
;         for (int a = 0; a < 2; ++a)
; #pragma unroll
;             for (int b = 0; b < 2; ++b)
; #pragma unroll
;                 for (int m = 0; m < 4; ++m)
; #pragma unroll
;                     for (int n = 0; n < 2; ++n) acc[a][b][m][n] = (f32x4){0.f, 0.f, 0.f, 0.f};
.LBB0_920:
	s_ashr_i32 s9, s8, 31
	s_lshl_b64 s[10:11], s[8:9], 19
	s_add_u32 s10, s70, s10
	s_addc_u32 s11, s71, s11
	s_and_b64 s[12:13], s[0:1], exec
	s_cselect_b32 s9, s11, s17
	s_cselect_b32 s38, s10, s16
	s_ashr_i32 s7, s6, 31
	s_lshl_b64 s[12:13], s[6:7], 19
	s_add_u32 s12, s23, s12
	s_addc_u32 s13, s24, s13
	s_and_b64 s[20:21], s[0:1], exec
	s_cselect_b32 s7, s13, s19
	s_cselect_b32 s39, s12, s18
	s_add_u32 s16, s16, 0x40080
	s_addc_u32 s17, s17, 0
	s_add_u32 s40, s18, 0x100
	v_mov_b32_e32 v0, 0
	s_addc_u32 s41, s19, 0
	s_mov_b32 s42, -2
	v_mov_b32_e32 v1, v0
	v_mov_b32_e32 v2, v0
	v_mov_b32_e32 v3, v0
	v_mov_b32_e32 v8, v0
	v_mov_b32_e32 v9, v0
	v_mov_b32_e32 v10, v0
	v_mov_b32_e32 v11, v0
	v_mov_b32_e32 v16, v0
	v_mov_b32_e32 v17, v0
	v_mov_b32_e32 v18, v0
	v_mov_b32_e32 v19, v0
	v_mov_b32_e32 v20, v0
	v_mov_b32_e32 v21, v0
	v_mov_b32_e32 v22, v0
	v_mov_b32_e32 v23, v0
	v_mov_b32_e32 v32, v0
	v_mov_b32_e32 v33, v0
	v_mov_b32_e32 v34, v0
	v_mov_b32_e32 v35, v0
	v_mov_b32_e32 v36, v0
	v_mov_b32_e32 v37, v0
	v_mov_b32_e32 v38, v0
	v_mov_b32_e32 v39, v0
	v_mov_b32_e32 v48, v0
	v_mov_b32_e32 v49, v0
	v_mov_b32_e32 v50, v0
	v_mov_b32_e32 v51, v0
	v_mov_b32_e32 v52, v0
	v_mov_b32_e32 v53, v0
	v_mov_b32_e32 v54, v0
	v_mov_b32_e32 v55, v0
	v_mov_b32_e32 v4, v0
	v_mov_b32_e32 v5, v0
	v_mov_b32_e32 v6, v0
	v_mov_b32_e32 v7, v0
	v_mov_b32_e32 v12, v0
	v_mov_b32_e32 v13, v0
	v_mov_b32_e32 v14, v0
	v_mov_b32_e32 v15, v0
	v_mov_b32_e32 v24, v0
	v_mov_b32_e32 v25, v0
	v_mov_b32_e32 v26, v0
	v_mov_b32_e32 v27, v0
	v_mov_b32_e32 v28, v0
	v_mov_b32_e32 v29, v0
	v_mov_b32_e32 v30, v0
	v_mov_b32_e32 v31, v0
	v_mov_b32_e32 v40, v0
	v_mov_b32_e32 v41, v0
	v_mov_b32_e32 v42, v0
	v_mov_b32_e32 v43, v0
	v_mov_b32_e32 v44, v0
	v_mov_b32_e32 v45, v0
	v_mov_b32_e32 v46, v0
	v_mov_b32_e32 v47, v0
	v_mov_b32_e32 v56, v0
	v_mov_b32_e32 v57, v0
	v_mov_b32_e32 v58, v0
	v_mov_b32_e32 v59, v0
	v_mov_b32_e32 v60, v0
	v_mov_b32_e32 v61, v0
	v_mov_b32_e32 v62, v0
	v_mov_b32_e32 v63, v0
	v_mov_b32_e32 v64, v0
	v_mov_b32_e32 v65, v0
	v_mov_b32_e32 v66, v0
	v_mov_b32_e32 v67, v0
	v_mov_b32_e32 v68, v0
	v_mov_b32_e32 v69, v0
	v_mov_b32_e32 v70, v0
	v_mov_b32_e32 v71, v0
	v_mov_b32_e32 v80, v0
	v_mov_b32_e32 v81, v0
	v_mov_b32_e32 v82, v0
	v_mov_b32_e32 v83, v0
	v_mov_b32_e32 v84, v0
	v_mov_b32_e32 v85, v0
	v_mov_b32_e32 v86, v0
	v_mov_b32_e32 v87, v0
	v_mov_b32_e32 v96, v0
	v_mov_b32_e32 v97, v0
	v_mov_b32_e32 v98, v0
	v_mov_b32_e32 v99, v0
	v_mov_b32_e32 v100, v0
	v_mov_b32_e32 v101, v0
	v_mov_b32_e32 v102, v0
	v_mov_b32_e32 v103, v0
	v_mov_b32_e32 v112, v0
	v_mov_b32_e32 v113, v0
	v_mov_b32_e32 v114, v0
	v_mov_b32_e32 v115, v0
	v_mov_b32_e32 v116, v0
	v_mov_b32_e32 v117, v0
	v_mov_b32_e32 v118, v0
	v_mov_b32_e32 v119, v0
	v_mov_b32_e32 v72, v0
	v_mov_b32_e32 v73, v0
	v_mov_b32_e32 v74, v0
	v_mov_b32_e32 v75, v0
	v_mov_b32_e32 v76, v0
	v_mov_b32_e32 v77, v0
	v_mov_b32_e32 v78, v0
	v_mov_b32_e32 v79, v0
	v_mov_b32_e32 v88, v0
	v_mov_b32_e32 v89, v0
	v_mov_b32_e32 v90, v0
	v_mov_b32_e32 v91, v0
	v_mov_b32_e32 v92, v0
	v_mov_b32_e32 v93, v0
	v_mov_b32_e32 v94, v0
	v_mov_b32_e32 v95, v0
	v_mov_b32_e32 v104, v0
	v_mov_b32_e32 v105, v0
	v_mov_b32_e32 v106, v0
	v_mov_b32_e32 v107, v0
	v_mov_b32_e32 v108, v0
	v_mov_b32_e32 v109, v0
	v_mov_b32_e32 v110, v0
	v_mov_b32_e32 v111, v0
	v_mov_b32_e32 v120, v0
	v_mov_b32_e32 v121, v0
	v_mov_b32_e32 v122, v0
	v_mov_b32_e32 v123, v0
	v_mov_b32_e32 v124, v0
	v_mov_b32_e32 v125, v0
	v_mov_b32_e32 v126, v0
	v_mov_b32_e32 v127, v0
	s_mov_b64 s[48:49], 0x80
	.p2alignl 8, 3212836864
